# out-projection phases: per-XCD start delay span 40 -> 55 us
# speedup vs baseline: 1.0026x; 1.0026x over previous
.LBB0_561:
	s_abs_i32 s3, s10
	v_cvt_f32_u32_e32 v0, s3
	s_sub_i32 s11, 0, s3
	v_rcp_iflag_f32_e32 v0, v0
	s_nop 0
	v_mul_f32_e32 v0, 0x4f7ffffe, v0
	v_cvt_u32_f32_e32 v0, v0
	s_nop 0
	v_readfirstlane_b32 s14, v0
	s_mul_i32 s11, s11, s14
	s_mul_hi_u32 s11, s14, s11
	s_add_i32 s14, s14, s11
	s_mul_hi_u32 s11, s14, 0x440
	s_mul_i32 s11, s11, s3
	s_sub_i32 s11, 0x440, s11
	s_sub_i32 s14, s11, s3
	s_cmp_ge_u32 s11, s3
	s_cselect_b32 s11, s14, s11
	s_sub_i32 s14, s11, s3
	s_cmp_ge_u32 s11, s3
	s_cselect_b32 s3, s14, s11
	s_cmp_eq_u32 s3, 0
	s_cbranch_scc1 .LBB0_559
	s_ashr_i32 s11, s10, 3
	s_abs_i32 s10, s11
	v_cvt_f32_u32_e32 v0, s10
	s_sub_i32 s16, 0, s10
	s_abs_i32 s14, s3
	s_xor_b32 s15, s3, s11
	v_rcp_iflag_f32_e32 v0, v0
	s_ashr_i32 s15, s15, 31
	v_mul_f32_e32 v0, 0x4f7ffffe, v0
	v_cvt_u32_f32_e32 v0, v0
	s_nop 0
	v_readfirstlane_b32 s17, v0
	s_mul_i32 s16, s16, s17
	s_mul_hi_u32 s16, s17, s16
	s_add_i32 s17, s17, s16
	s_mul_hi_u32 s16, s14, s17
	s_mul_i32 s17, s16, s10
	s_sub_i32 s14, s14, s17
	s_add_i32 s18, s16, 1
	s_sub_i32 s17, s14, s10
	s_cmp_ge_u32 s14, s10
	s_cselect_b32 s16, s18, s16
	s_cselect_b32 s14, s17, s14
	s_add_i32 s17, s16, 1
	s_cmp_ge_u32 s14, s10
	s_cselect_b32 s10, s17, s16
	s_xor_b32 s10, s10, s15
	s_sub_i32 s10, s10, s15
	s_mul_i32 s11, s10, s11
	s_sub_i32 s3, s3, s11
	s_cmp_lg_u32 s3, 0
	s_cbranch_scc1 .LBB0_559
	s_and_b32 s2, s2, 7
	s_cmp_lt_i32 s2, s10
	s_cbranch_scc1 .LBB0_559
	s_sub_i32 s2, s2, s10
	v_cvt_f32_i32_e32 v0, s2
	s_sub_i32 s2, 8, s10
	v_cvt_f32_u32_e32 v1, s2
	v_mul_f32_e32 v0, 0x45abe000, v0
	v_div_scale_f32 v2, s[2:3], v1, v1, v0
	v_rcp_f32_e32 v3, v2
	v_div_scale_f32 v4, vcc, v0, v1, v0
	s_memrealtime s[2:3]
	v_fma_f32 v5, -v2, v3, 1.0
	v_fmac_f32_e32 v3, v5, v3
	v_mul_f32_e32 v5, v4, v3
	v_fma_f32 v6, -v2, v5, v4
	v_fmac_f32_e32 v5, v6, v3
	v_fma_f32 v2, -v2, v5, v4
	v_div_fmas_f32 v2, v2, v3, v5
	v_div_fixup_f32 v0, v2, v1, v0
	v_trunc_f32_e32 v0, v0
	v_mul_f32_e32 v1, 0x2f800000, v0
	v_floor_f32_e32 v1, v1
	v_fmac_f32_e32 v0, 0xcf800000, v1
	v_cvt_u32_f32_e32 v0, v0
	v_cvt_u32_f32_e32 v1, v1
	s_memrealtime s[10:11]
	s_waitcnt lgkmcnt(0)
	v_lshl_add_u64 v[0:1], s[2:3], 0, v[0:1]
	v_cmp_ge_u64_e32 vcc, s[10:11], v[0:1]
	s_cbranch_vccnz .LBB0_559

.LBB0_931:
	s_abs_i32 s3, s8
	v_cvt_f32_u32_e32 v0, s3
	s_sub_i32 s9, 0, s3
	v_rcp_iflag_f32_e32 v0, v0
	s_nop 0
	v_mul_f32_e32 v0, 0x4f7ffffe, v0
	v_cvt_u32_f32_e32 v0, v0
	s_nop 0
	v_readfirstlane_b32 s10, v0
	s_mul_i32 s9, s9, s10
	s_mul_hi_u32 s9, s10, s9
	s_add_i32 s10, s10, s9
	s_mul_hi_u32 s9, s10, 0x440
	s_mul_i32 s9, s9, s3
	s_sub_i32 s9, 0x440, s9
	s_sub_i32 s10, s9, s3
	s_cmp_ge_u32 s9, s3
	s_cselect_b32 s9, s10, s9
	s_sub_i32 s10, s9, s3
	s_cmp_ge_u32 s9, s3
	s_cselect_b32 s3, s10, s9
	s_cmp_eq_u32 s3, 0
	s_cbranch_scc1 .LBB0_929
	s_ashr_i32 s9, s8, 3
	s_abs_i32 s8, s9
	v_cvt_f32_u32_e32 v0, s8
	s_sub_i32 s14, 0, s8
	s_abs_i32 s10, s3
	s_xor_b32 s11, s3, s9
	v_rcp_iflag_f32_e32 v0, v0
	s_ashr_i32 s11, s11, 31
	v_mul_f32_e32 v0, 0x4f7ffffe, v0
	v_cvt_u32_f32_e32 v0, v0
	s_nop 0
	v_readfirstlane_b32 s15, v0
	s_mul_i32 s14, s14, s15
	s_mul_hi_u32 s14, s15, s14
	s_add_i32 s15, s15, s14
	s_mul_hi_u32 s14, s10, s15
	s_mul_i32 s15, s14, s8
	s_sub_i32 s10, s10, s15
	s_add_i32 s16, s14, 1
	s_sub_i32 s15, s10, s8
	s_cmp_ge_u32 s10, s8
	s_cselect_b32 s14, s16, s14
	s_cselect_b32 s10, s15, s10
	s_add_i32 s15, s14, 1
	s_cmp_ge_u32 s10, s8
	s_cselect_b32 s8, s15, s14
	s_xor_b32 s8, s8, s11
	s_sub_i32 s8, s8, s11
	s_mul_i32 s9, s8, s9
	s_sub_i32 s3, s3, s9
	s_cmp_lg_u32 s3, 0
	s_cbranch_scc1 .LBB0_929
	s_and_b32 s2, s2, 7
	s_cmp_lt_i32 s2, s8
	s_cbranch_scc1 .LBB0_929
	s_sub_i32 s2, s2, s8
	v_cvt_f32_i32_e32 v0, s2
	s_sub_i32 s2, 8, s8
	v_cvt_f32_u32_e32 v1, s2
	v_mul_f32_e32 v0, 0x45abe000, v0
	v_div_scale_f32 v2, s[2:3], v1, v1, v0
	v_rcp_f32_e32 v3, v2
	v_div_scale_f32 v4, vcc, v0, v1, v0
	s_memrealtime s[2:3]
	v_fma_f32 v5, -v2, v3, 1.0
	v_fmac_f32_e32 v3, v5, v3
	v_mul_f32_e32 v5, v4, v3
	v_fma_f32 v6, -v2, v5, v4
	v_fmac_f32_e32 v5, v6, v3
	v_fma_f32 v2, -v2, v5, v4
	v_div_fmas_f32 v2, v2, v3, v5
	v_div_fixup_f32 v0, v2, v1, v0
	v_trunc_f32_e32 v0, v0
	v_mul_f32_e32 v1, 0x2f800000, v0
	v_floor_f32_e32 v1, v1
	v_fmac_f32_e32 v0, 0xcf800000, v1
	v_cvt_u32_f32_e32 v0, v0
	v_cvt_u32_f32_e32 v1, v1
	s_memrealtime s[8:9]
	s_waitcnt lgkmcnt(0)
	v_lshl_add_u64 v[0:1], s[2:3], 0, v[0:1]
	v_cmp_ge_u64_e32 vcc, s[8:9], v[0:1]
	s_cbranch_vccnz .LBB0_929
